# k33: attention unit order within each equal-work pair swapped (long query block first) so the four workgroups of a head sweep the same K/V tiles together right after the phase barrier
# speedup vs baseline: 1.0030x; 1.0030x over previous
.LBB0_1328:
	s_lshl_b32 s4, s88, 1
	s_and_b32 s4, s4, 12
	s_or_b32 s4, s4, s33
	v_mov_b32_e32 v48, v226
	s_lshl_b32 s4, s4, 8
	v_readfirstlane_b32 s5, v48
	s_and_b32 s6, s88, 1
	s_ashr_i32 s74, s5, 6
	s_xor_b32 s7, s4, 0x1f00
	s_cmp_eq_u32 s6, 0
	s_cselect_b32 s68, s7, s4
	s_lshl_b32 s10, s74, 5
	s_or_b32 s71, s68, s40
	s_ashr_i32 s4, s10, 31
	s_add_u32 s6, s10, s71
	s_addc_u32 s7, s4, 0
	s_lshl_b64 s[6:7], s[6:7], 11
	v_and_b32_e32 v231, 63, v48
	s_add_u32 s6, s42, s6
	s_addc_u32 s7, s43, s7
	v_lshlrev_b32_e32 v212, 11, v231
	s_lshl_b32 s8, s74, 3
	v_lshl_add_u64 v[0:1], s[28:29], 0, v[212:213]
	s_ashr_i32 s9, s8, 31
	v_lshl_add_u64 v[214:215], s[8:9], 1, v[0:1]
	s_lshl_b32 s4, s74, 4
	v_bfe_u32 v0, v48, 2, 4
	v_and_or_b32 v0, s4, 48, v0
	s_ashr_i32 s4, s5, 3
	s_and_b32 s8, s4, 0xffffffe0
	v_lshlrev_b32_e32 v212, 11, v0
	s_ashr_i32 s9, s8, 31
	s_lshl_b32 s4, s74, 10
	v_lshl_add_u64 v[0:1], s[30:31], 0, v[212:213]
	v_lshlrev_b32_e32 v2, 3, v48
	s_cmp_lg_u32 0, -1
	v_lshl_add_u64 v[0:1], s[8:9], 1, v[0:1]
	v_and_b32_e32 v232, 24, v2
	s_cselect_b32 s8, 0, 0
	v_lshlrev_b32_e32 v212, 1, v232
	s_add_i32 s76, s4, s8
	s_mov_b32 m0, s76
	s_nop 0
	global_load_lds_dwordx4 v[214:215], off
	v_lshl_add_u64 v[216:217], v[0:1], 0, v[212:213]
	s_add_i32 s77, s76, 0x6000
	s_mov_b32 m0, s77
	s_nop 0
	global_load_lds_dwordx4 v[216:217], off
	v_and_b32_e32 v230, 31, v48
	v_lshl_add_u64 v[218:219], v[216:217], 0, s[12:13]
	s_add_i32 s8, s76, 0x8000
	s_mov_b32 m0, s8
	s_nop 0
	global_load_lds_dwordx4 v[218:219], off
	v_lshl_add_u64 v[0:1], v[214:215], 0, s[14:15]
	v_bfe_u32 v242, v48, 5, 1
	s_add_i32 s8, s76, 0x2000
	s_mov_b32 m0, s8
	s_nop 0
	global_load_lds_dwordx4 v[0:1], off
	v_lshlrev_b32_e32 v0, 11, v230
	v_lshl_or_b32 v0, v242, 4, v0
	global_load_dwordx4 v[172:175], v0, s[6:7]
	global_load_dwordx4 v[168:171], v0, s[6:7] offset:32
	global_load_dwordx4 v[160:163], v0, s[6:7] offset:64
	global_load_dwordx4 v[152:155], v0, s[6:7] offset:96
	v_lshlrev_b32_e32 v1, 10, v242
	v_lshlrev_b32_e32 v2, 4, v230
	v_mov_b32 v0, 0
	v_add3_u32 v238, 0, v1, v2
	v_mov_b32_e32 v14, v0
	v_mov_b32_e32 v15, v0
	v_mov_b32_e32 v1, v0
	v_mov_b32_e32 v2, v0
	v_mov_b32_e32 v3, v0
	v_mov_b32_e32 v4, v0
	v_mov_b32_e32 v5, v0
	v_mov_b32_e32 v6, v0
	v_mov_b32_e32 v7, v0
	v_mov_b32_e32 v8, v0
	v_mov_b32_e32 v9, v0
	v_mov_b32_e32 v10, v0
	v_mov_b32_e32 v11, v0
	v_mov_b32_e32 v12, v0
	v_mov_b32_e32 v13, v0
	v_mov_b64_e32 v[30:31], v[14:15]
	v_mov_b64_e32 v[28:29], v[12:13]
	v_mov_b64_e32 v[26:27], v[10:11]
	v_mov_b64_e32 v[24:25], v[8:9]
	v_mov_b64_e32 v[22:23], v[6:7]
	v_mov_b64_e32 v[20:21], v[4:5]
	v_mov_b64_e32 v[18:19], v[2:3]
	v_mov_b64_e32 v[16:17], v[0:1]
	v_lshl_add_u64 v[32:33], v[214:215], 0, s[16:17]
	s_add_i32 s8, s76, 0x4000
	s_mov_b32 m0, s8
	s_nop 0
	global_load_lds_dwordx4 v[32:33], off
	s_waitcnt vmcnt(3) lgkmcnt(0)
	s_barrier
	ds_read_b128 v[50:53], v238
	ds_read_b128 v[54:57], v238 offset:512
	s_cmp_eq_u32 s68, 0
	s_cselect_b64 s[34:35], -1, 0
	s_cmp_lg_u32 s68, 0
	s_cselect_b64 s[8:9], -1, 0
	v_lshlrev_b32_e32 v212, 2, v242
	v_or_b32_e32 v236, s10, v230
	s_and_b64 vcc, exec, s[8:9]
	s_waitcnt vmcnt(3) lgkmcnt(1)
	v_mfma_f32_32x32x16_bf16 v[32:47], v[50:53], v[172:175], v[16:31]
	s_waitcnt lgkmcnt(0)
	v_mfma_f32_32x32x16_bf16 v[16:31], v[54:57], v[172:175], v[16:31]
	ds_read_b128 v[50:53], v238 offset:2048
	ds_read_b128 v[54:57], v238 offset:2560
	s_waitcnt vmcnt(2) lgkmcnt(1)
	v_mfma_f32_32x32x16_bf16 v[32:47], v[50:53], v[168:171], v[32:47]
	s_waitcnt lgkmcnt(0)
	v_mfma_f32_32x32x16_bf16 v[16:31], v[54:57], v[168:171], v[16:31]
	ds_read_b128 v[50:53], v238 offset:4096
	ds_read_b128 v[54:57], v238 offset:4608
	s_waitcnt vmcnt(1) lgkmcnt(1)
	v_mfma_f32_32x32x16_bf16 v[32:47], v[50:53], v[160:163], v[32:47]
	s_waitcnt lgkmcnt(0)
	v_mfma_f32_32x32x16_bf16 v[16:31], v[54:57], v[160:163], v[16:31]
	ds_read_b128 v[50:53], v238 offset:6144
	ds_read_b128 v[54:57], v238 offset:6656
	s_waitcnt vmcnt(0) lgkmcnt(1)
	v_mfma_f32_32x32x16_bf16 v[32:47], v[50:53], v[152:155], v[32:47]
	s_waitcnt lgkmcnt(0)
	v_mfma_f32_32x32x16_bf16 v[16:31], v[54:57], v[152:155], v[16:31]
	s_nop 15
	s_nop 7
	s_cbranch_vccnz .LBB0_1330
	v_lshlrev_b32_e32 v49, 2, v242
	v_or_b32_e32 v50, 32, v49
	v_cmp_le_i32_e32 vcc, v50, v236
	v_or_b32_e32 v50, 33, v49
	s_nop 6
	v_cndmask_b32_e32 v16, v228, v16, vcc
	v_cmp_lt_i32_e32 vcc, v49, v236
	s_nop 1
	v_cndmask_b32_e32 v33, v228, v33, vcc
	v_cmp_le_i32_e32 vcc, v49, v236
	s_nop 1
	v_cndmask_b32_e32 v32, v228, v32, vcc
	v_cmp_le_i32_e32 vcc, v50, v236
	v_or_b32_e32 v50, 2, v49
	s_nop 0
	v_cndmask_b32_e32 v17, v228, v17, vcc
	v_cmp_le_i32_e32 vcc, v50, v236
	v_or_b32_e32 v50, 34, v49
	s_nop 0
	v_cndmask_b32_e32 v34, v228, v34, vcc
	v_cmp_le_i32_e32 vcc, v50, v236
	v_or_b32_e32 v50, 3, v49
	s_nop 0
	v_cndmask_b32_e32 v18, v228, v18, vcc
	v_cmp_le_i32_e32 vcc, v50, v236
	v_or_b32_e32 v50, 35, v49
	s_nop 0
	v_cndmask_b32_e32 v35, v228, v35, vcc
	v_cmp_le_i32_e32 vcc, v50, v236
	v_or_b32_e32 v50, 8, v49
	s_nop 0
	v_cndmask_b32_e32 v19, v228, v19, vcc
	v_cmp_le_i32_e32 vcc, v50, v236
	v_or_b32_e32 v50, 40, v49
	s_nop 0
	v_cndmask_b32_e32 v36, v228, v36, vcc
	v_cmp_le_i32_e32 vcc, v50, v236
	v_or_b32_e32 v50, 9, v49
	s_nop 0
	v_cndmask_b32_e32 v20, v228, v20, vcc
	v_cmp_le_i32_e32 vcc, v50, v236
	v_or_b32_e32 v50, 41, v49
	s_nop 0
	v_cndmask_b32_e32 v37, v228, v37, vcc
	v_cmp_le_i32_e32 vcc, v50, v236
	v_or_b32_e32 v50, 10, v49
	s_nop 0
	v_cndmask_b32_e32 v21, v228, v21, vcc
	v_cmp_le_i32_e32 vcc, v50, v236
	v_or_b32_e32 v50, 42, v49
	s_nop 0
	v_cndmask_b32_e32 v38, v228, v38, vcc
	v_cmp_le_i32_e32 vcc, v50, v236
	v_or_b32_e32 v50, 11, v49
	s_nop 0
	v_cndmask_b32_e32 v22, v228, v22, vcc
	v_cmp_le_i32_e32 vcc, v50, v236
	v_or_b32_e32 v50, 43, v49
	s_nop 0
	v_cndmask_b32_e32 v39, v228, v39, vcc
	v_cmp_le_i32_e32 vcc, v50, v236
	v_or_b32_e32 v50, 16, v49
	s_nop 0
	v_cndmask_b32_e32 v23, v228, v23, vcc
	v_cmp_le_i32_e32 vcc, v50, v236
	v_or_b32_e32 v50, 48, v49
	s_nop 0
	v_cndmask_b32_e32 v40, v228, v40, vcc
	v_cmp_le_i32_e32 vcc, v50, v236
	v_or_b32_e32 v50, 17, v49
	s_nop 0
	v_cndmask_b32_e32 v24, v228, v24, vcc
	v_cmp_le_i32_e32 vcc, v50, v236
	v_or_b32_e32 v50, 49, v49
	s_nop 0
	v_cndmask_b32_e32 v41, v228, v41, vcc
	v_cmp_le_i32_e32 vcc, v50, v236
	v_or_b32_e32 v50, 18, v49
	s_nop 0
	v_cndmask_b32_e32 v25, v228, v25, vcc
	v_cmp_le_i32_e32 vcc, v50, v236
	v_or_b32_e32 v50, 50, v49
	s_nop 0
	v_cndmask_b32_e32 v42, v228, v42, vcc
	v_cmp_le_i32_e32 vcc, v50, v236
	v_or_b32_e32 v50, 19, v49
	s_nop 0
	v_cndmask_b32_e32 v26, v228, v26, vcc
	v_cmp_le_i32_e32 vcc, v50, v236
	v_or_b32_e32 v50, 51, v49
	s_nop 0
	v_cndmask_b32_e32 v43, v228, v43, vcc
	v_cmp_le_i32_e32 vcc, v50, v236
	v_or_b32_e32 v50, 24, v49
	s_nop 0
	v_cndmask_b32_e32 v27, v228, v27, vcc
	v_cmp_le_i32_e32 vcc, v50, v236
	v_or_b32_e32 v50, 56, v49
	s_nop 0
	v_cndmask_b32_e32 v44, v228, v44, vcc
	v_cmp_le_i32_e32 vcc, v50, v236
	v_or_b32_e32 v50, 25, v49
	s_nop 0
	v_cndmask_b32_e32 v28, v228, v28, vcc
	v_cmp_le_i32_e32 vcc, v50, v236
	v_or_b32_e32 v50, 57, v49
	s_nop 0
	v_cndmask_b32_e32 v45, v228, v45, vcc
	v_cmp_le_i32_e32 vcc, v50, v236
	v_or_b32_e32 v50, 26, v49
	s_nop 0
	v_cndmask_b32_e32 v29, v228, v29, vcc
	v_cmp_le_i32_e32 vcc, v50, v236
	v_or_b32_e32 v50, 58, v49
	s_nop 0
	v_cndmask_b32_e32 v46, v228, v46, vcc
	v_cmp_le_i32_e32 vcc, v50, v236
	v_or_b32_e32 v50, 27, v49
	v_or_b32_e32 v49, 59, v49
	v_cndmask_b32_e32 v30, v228, v30, vcc
	v_cmp_le_i32_e32 vcc, v50, v236
	s_nop 1
	v_cndmask_b32_e32 v47, v228, v47, vcc
	v_cmp_le_i32_e32 vcc, v49, v236
	s_nop 1
	v_cndmask_b32_e32 v31, v228, v31, vcc
